# la_lb: loop-invariant log-base loads removed from the la_range_out chunk loop (2 fewer vector-memory instructions per chunk), on p11pos+sel_ip
# speedup vs baseline: 1.0076x; 1.0076x over previous
.LBB0_450:
	s_or_b64 exec, exec, s[68:69]
	s_waitcnt lgkmcnt(0)
	ds_read_b128 v[84:87], v147
	ds_read_b128 v[88:91], v147 offset:64
	ds_read_b128 v[92:95], v147 offset:128
	s_and_b32 s68, s3, 0x1fc0
	s_add_u32 s64, s64, 1
	s_waitcnt lgkmcnt(2)
	v_pk_mul_f32 v[30:31], v[30:31], v[86:87]
	s_waitcnt lgkmcnt(1)
	v_pk_mul_f32 v[26:27], v[26:27], v[90:91]
	v_pk_mul_f32 v[24:25], v[24:25], v[88:89]
	ds_read_b128 v[88:91], v164
	v_pk_mul_f32 v[28:29], v[28:29], v[84:85]
	ds_read_b128 v[84:87], v147 offset:192
	s_waitcnt lgkmcnt(2)
	v_pk_mul_f32 v[22:23], v[22:23], v[94:95]
	v_pk_mul_f32 v[20:21], v[20:21], v[92:93]
	ds_read_b128 v[92:95], v148 offset:55296
	s_addc_u32 s65, s65, 0
	s_waitcnt lgkmcnt(1)
	v_pk_mul_f32 v[18:19], v[18:19], v[86:87]
	v_pk_mul_f32 v[16:17], v[16:17], v[84:85]
	ds_read_b128 v[84:87], v164 offset:2560
	ds_read_b128 v[96:99], v148 offset:55360
	ds_read_b128 v[100:103], v164 offset:64
	s_waitcnt lgkmcnt(3)
	v_mfma_f32_16x16x32_bf16 v[28:31], v[88:91], v[92:95], v[28:31]
	ds_read_b128 v[88:91], v164 offset:5120
	ds_read_b128 v[104:107], v147 offset:256
	ds_read_b128 v[108:111], v147 offset:320
	ds_read_b128 v[112:115], v164 offset:7680
	ds_read_b128 v[116:119], v164 offset:2624
	s_add_i32 s3, s3, 64
	s_waitcnt lgkmcnt(3)
	v_pk_mul_f32 v[14:15], v[14:15], v[106:107]
	v_mfma_f32_16x16x32_bf16 v[24:27], v[84:87], v[92:95], v[24:27]
	ds_read_b128 v[84:87], v164 offset:10240
	ds_read_b128 v[120:123], v164 offset:5184
	v_pk_mul_f32 v[12:13], v[12:13], v[104:105]
	ds_read_b128 v[104:107], v164 offset:12800
	v_mfma_f32_16x16x32_bf16 v[20:23], v[88:91], v[92:95], v[20:23]
	ds_read_b128 v[88:91], v164 offset:7744
	s_waitcnt lgkmcnt(6)
	v_pk_mul_f32 v[10:11], v[10:11], v[110:111]
	v_pk_mul_f32 v[8:9], v[8:9], v[108:109]
	s_waitcnt lgkmcnt(5)
	v_mfma_f32_16x16x32_bf16 v[16:19], v[112:115], v[92:95], v[16:19]
	ds_read_b128 v[108:111], v164 offset:10304
	s_cmp_eq_u32 s64, 16
	s_waitcnt vmcnt(0)
	s_waitcnt lgkmcnt(4)
	v_mfma_f32_16x16x32_bf16 v[12:15], v[84:87], v[92:95], v[12:15]
	ds_read_b128 v[84:87], v164 offset:15360
	ds_read_b128 v[112:115], v147 offset:384
	ds_read_b128 v[124:127], v147 offset:448
	ds_read_b128 v[132:135], v164 offset:17920
	ds_read_b128 v[168:171], v164 offset:12864
	s_waitcnt lgkmcnt(3)
	v_pk_mul_f32 v[2:3], v[2:3], v[114:115]
	v_pk_mul_f32 v[0:1], v[0:1], v[112:113]
	v_mfma_f32_16x16x32_bf16 v[8:11], v[104:107], v[92:95], v[8:11]
	ds_read_b128 v[104:107], v164 offset:15424
	s_waitcnt lgkmcnt(3)
	v_pk_mul_f32 v[6:7], v[6:7], v[126:127]
	v_pk_mul_f32 v[4:5], v[4:5], v[124:125]
	v_mfma_f32_16x16x32_bf16 v[0:3], v[84:87], v[92:95], v[0:3]
	ds_read_b128 v[84:87], v164 offset:17984
	s_waitcnt lgkmcnt(0)
	s_barrier
	v_mfma_f32_16x16x32_bf16 v[16:19], v[88:91], v[96:99], v[16:19]
	ds_read2st64_b32 v[88:89], v141 offset1:1
	s_waitcnt lgkmcnt(0)
	v_add_f32_e32 v88, v88, v89
	v_mfma_f32_16x16x32_bf16 v[4:7], v[132:135], v[92:95], v[4:7]
	v_fmamk_f32 v88, v88, 0x3c000000, v165
	v_mul_f32_e32 v89, 0x4b800000, v88
	v_cmp_gt_f32_e32 vcc, s76, v88
	v_mfma_f32_16x16x32_bf16 v[4:7], v[84:87], v[96:99], v[4:7]
	s_nop 0
	v_cndmask_b32_e32 v88, v88, v89, vcc
	v_rsq_f32_e32 v90, v88
	ds_read2_b64 v[86:89], v152 offset1:4
	v_mfma_f32_16x16x32_bf16 v[28:31], v[100:103], v[96:99], v[28:31]
	v_mul_f32_e32 v84, 0x45800000, v90
	v_cndmask_b32_e32 v84, v90, v84, vcc
	s_waitcnt lgkmcnt(0)
	v_lshlrev_b32_e32 v100, 16, v86
	v_and_b32_e32 v101, 0xffff0000, v86
	v_mul_f32_e32 v85, 0xbfb8aa3b, v100
	v_exp_f32_e32 v85, v85
	v_mul_f32_e32 v86, 0xbfb8aa3b, v101
	v_exp_f32_e32 v86, v86
	v_or_b32_e32 v90, s68, v153
	v_ashrrev_i32_e32 v91, 31, v90
	v_add_f32_e32 v85, 1.0, v85
	v_mfma_f32_16x16x32_bf16 v[24:27], v[116:119], v[96:99], v[24:27]
	v_rcp_f32_e32 v102, v85
	v_add_f32_e32 v85, 1.0, v86
	v_rcp_f32_e32 v103, v85
	v_mfma_f32_16x16x32_bf16 v[20:23], v[120:123], v[96:99], v[20:23]
	v_lshlrev_b32_e32 v86, 16, v87
	v_pk_mul_f32 v[76:77], v[76:77], v[84:85] op_sel_hi:[1,0]
	v_and_b32_e32 v87, 0xffff0000, v87
	v_mfma_f32_16x16x32_bf16 v[12:15], v[108:111], v[96:99], v[12:15]
	v_mul_f32_e32 v85, 0xbfb8aa3b, v86
	v_exp_f32_e32 v85, v85
	v_mfma_f32_16x16x32_bf16 v[8:11], v[168:171], v[96:99], v[8:11]
	v_add_f32_e32 v85, 1.0, v85
	v_mfma_f32_16x16x32_bf16 v[0:3], v[104:107], v[96:99], v[0:3]
	v_lshlrev_b64 v[98:99], 11, v[90:91]
	ds_read_b128 v[90:93], v151
	ds_read_b128 v[94:97], v151 offset:64
	s_waitcnt lgkmcnt(1)
	v_pk_mul_f32 v[76:77], v[90:91], v[76:77]
	v_pk_mul_f32 v[90:91], v[102:103], v[100:101]
	v_mul_f32_e32 v100, 0xbfb8aa3b, v87
	v_exp_f32_e32 v100, v100
	v_pk_mul_f32 v[76:77], v[76:77], v[90:91]
	v_rcp_f32_e32 v90, v85
	v_cvt_pk_bf16_f32 v76, v76, v77
	v_add_f32_e32 v85, 1.0, v100
	v_rcp_f32_e32 v91, v85
	v_pk_mul_f32 v[78:79], v[78:79], v[84:85] op_sel_hi:[1,0]
	v_pk_mul_f32 v[86:87], v[90:91], v[86:87]
	v_pk_mul_f32 v[78:79], v[92:93], v[78:79]
	v_lshl_add_u64 v[90:91], v[82:83], 0, v[98:99]
	v_pk_mul_f32 v[78:79], v[78:79], v[86:87]
	s_nop 0
	v_cvt_pk_bf16_f32 v77, v78, v79
	v_lshlrev_b32_e32 v78, 16, v88
	v_and_b32_e32 v79, 0xffff0000, v88
	v_mul_f32_e32 v85, 0xbfb8aa3b, v78
	v_exp_f32_e32 v85, v85
	v_mul_f32_e32 v86, 0xbfb8aa3b, v79
	v_exp_f32_e32 v87, v86
	global_store_dwordx2 v[90:91], v[76:77], off
	v_add_f32_e32 v85, 1.0, v85
	v_rcp_f32_e32 v86, v85
	v_add_f32_e32 v85, 1.0, v87
	v_rcp_f32_e32 v87, v85
	v_pk_mul_f32 v[72:73], v[72:73], v[84:85] op_sel_hi:[1,0]
	v_pk_mul_f32 v[76:77], v[86:87], v[78:79]
	s_waitcnt lgkmcnt(0)
	v_pk_mul_f32 v[72:73], v[94:95], v[72:73]
	s_nop 0
	v_pk_mul_f32 v[72:73], v[72:73], v[76:77]
	v_lshlrev_b32_e32 v76, 16, v89
	v_and_b32_e32 v77, 0xffff0000, v89
	v_mul_f32_e32 v78, 0xbfb8aa3b, v76
	v_exp_f32_e32 v79, v78
	v_mul_f32_e32 v78, 0xbfb8aa3b, v77
	v_exp_f32_e32 v85, v78
	v_cvt_pk_bf16_f32 v78, v72, v73
	v_add_f32_e32 v72, 1.0, v79
	v_rcp_f32_e32 v86, v72
	v_add_f32_e32 v72, 1.0, v85
	v_rcp_f32_e32 v87, v72
	v_pk_mul_f32 v[72:73], v[74:75], v[84:85] op_sel_hi:[1,0]
	v_pk_mul_f32 v[76:77], v[86:87], v[76:77]
	v_pk_mul_f32 v[88:89], v[96:97], v[72:73]
	ds_read2_b64 v[72:75], v152 offset0:8 offset1:12
	v_pk_mul_f32 v[76:77], v[88:89], v[76:77]
	ds_read_b128 v[86:89], v151 offset:192
	v_cvt_pk_bf16_f32 v79, v76, v77
	global_store_dwordx2 v[90:91], v[78:79], off offset:32
	s_waitcnt lgkmcnt(1)
	v_lshlrev_b32_e32 v92, 16, v72
	v_and_b32_e32 v93, 0xffff0000, v72
	v_mul_f32_e32 v72, 0xbfb8aa3b, v92
	v_exp_f32_e32 v72, v72
	v_mul_f32_e32 v76, 0xbfb8aa3b, v93
	v_exp_f32_e32 v85, v76
	ds_read_b128 v[76:79], v151 offset:128
	v_add_f32_e32 v72, 1.0, v72
	v_rcp_f32_e32 v94, v72
	v_add_f32_e32 v72, 1.0, v85
	v_rcp_f32_e32 v95, v72
	v_pk_mul_f32 v[68:69], v[68:69], v[84:85] op_sel_hi:[1,0]
	v_lshlrev_b32_e32 v72, 16, v73
	v_and_b32_e32 v73, 0xffff0000, v73
	s_waitcnt lgkmcnt(0)
	v_pk_mul_f32 v[68:69], v[76:77], v[68:69]
	v_pk_mul_f32 v[76:77], v[94:95], v[92:93]
	v_mul_f32_e32 v85, 0xbfb8aa3b, v72
	v_mul_f32_e32 v92, 0xbfb8aa3b, v73
	v_exp_f32_e32 v85, v85
	v_exp_f32_e32 v92, v92
	v_pk_mul_f32 v[68:69], v[68:69], v[76:77]
	v_add_f32_e32 v76, 1.0, v85
	v_add_f32_e32 v77, 1.0, v92
	v_rcp_f32_e32 v76, v76
	v_rcp_f32_e32 v77, v77
	v_pk_mul_f32 v[70:71], v[70:71], v[84:85] op_sel_hi:[1,0]
	v_cvt_pk_bf16_f32 v68, v68, v69
	v_pk_mul_f32 v[70:71], v[78:79], v[70:71]
	v_pk_mul_f32 v[72:73], v[76:77], v[72:73]
	v_pk_mul_f32 v[64:65], v[64:65], v[84:85] op_sel_hi:[1,0]
	v_pk_mul_f32 v[70:71], v[70:71], v[72:73]
	v_lshlrev_b32_e32 v72, 16, v74
	v_and_b32_e32 v73, 0xffff0000, v74
	v_mul_f32_e32 v69, 0xbfb8aa3b, v72
	v_exp_f32_e32 v74, v69
	v_mul_f32_e32 v69, 0xbfb8aa3b, v73
	v_exp_f32_e32 v76, v69
	v_cvt_pk_bf16_f32 v69, v70, v71
	v_add_f32_e32 v70, 1.0, v74
	v_rcp_f32_e32 v70, v70
	v_add_f32_e32 v71, 1.0, v76
	v_rcp_f32_e32 v71, v71
	global_store_dwordx2 v[90:91], v[68:69], off offset:64
	v_pk_mul_f32 v[64:65], v[64:65], v[86:87]
	v_pk_mul_f32 v[66:67], v[66:67], v[84:85] op_sel_hi:[1,0]
	v_pk_mul_f32 v[68:69], v[70:71], v[72:73]
	v_lshlrev_b32_e32 v70, 16, v75
	v_and_b32_e32 v71, 0xffff0000, v75
	v_mul_f32_e32 v72, 0xbfb8aa3b, v70
	v_mul_f32_e32 v73, 0xbfb8aa3b, v71
	v_exp_f32_e32 v72, v72
	v_exp_f32_e32 v73, v73
	v_pk_mul_f32 v[64:65], v[64:65], v[68:69]
	v_pk_mul_f32 v[66:67], v[66:67], v[88:89]
	v_add_f32_e32 v68, 1.0, v72
	v_add_f32_e32 v69, 1.0, v73
	v_rcp_f32_e32 v68, v68
	v_rcp_f32_e32 v69, v69
	v_cvt_pk_bf16_f32 v64, v64, v65
	v_pk_mul_f32 v[68:69], v[68:69], v[70:71]
	s_nop 0
	v_pk_mul_f32 v[66:67], v[66:67], v[68:69]
	s_nop 0
	v_cvt_pk_bf16_f32 v65, v66, v67
	global_store_dwordx2 v[90:91], v[64:65], off offset:96
	s_waitcnt lgkmcnt(0)
	s_barrier
	ds_write_b128 v137, v[32:35]
	ds_write_b128 v137, v[36:39] offset:18432
	ds_write_b128 v137, v[40:43] offset:36864
	ds_write_b128 v139, v[44:47]
	ds_write_b128 v138, v[48:51]
	ds_write_b128 v138, v[52:55] offset:18432
	ds_write_b128 v138, v[56:59] offset:36864
	ds_write_b128 v140, v[60:63]
	s_waitcnt lgkmcnt(0)
	s_barrier
	s_cbranch_scc1 .LBB0_463
.LBB0_451:
	s_cmp_lg_u32 s64, 15
	s_cselect_b64 s[68:69], -1, 0
	s_cmp_lg_u64 s[68:69], 0
	s_addc_u32 s82, s56, s64
	v_cndmask_b32_e64 v32, 0, 1, s[68:69]
	s_add_u32 s68, s56, s64
	v_mov_b32_e32 v33, s81
	s_addc_u32 s69, s57, s65
	v_lshl_add_u64 v[32:33], s[68:69], 0, v[32:33]
	v_lshlrev_b64 v[32:33], 16, v[32:33]
	v_lshl_add_u64 v[32:33], s[54:55], 0, v[32:33]
	v_lshl_add_u64 v[60:61], v[32:33], 0, v[80:81]
	v_add_co_u32_e32 v36, vcc, s67, v60
	s_and_b32 s82, s82, 0x180
	s_nop 0
	v_addc_co_u32_e32 v37, vcc, 0, v61, vcc
	v_add_co_u32_e32 v40, vcc, s70, v60
	v_or_b32_e32 v64, s82, v136
	s_nop 0
	v_addc_co_u32_e32 v41, vcc, 0, v61, vcc
	v_add_co_u32_e32 v44, vcc, s71, v60
	v_readfirstlane_b32 s68, v32
	s_nop 0
	v_addc_co_u32_e32 v45, vcc, 0, v61, vcc
	v_add_co_u32_e32 v48, vcc, s77, v60
	v_readfirstlane_b32 s69, v33
	s_nop 0
	v_addc_co_u32_e32 v49, vcc, 0, v61, vcc
	v_add_co_u32_e32 v52, vcc, s78, v60
	v_lshlrev_b32_e32 v64, 2, v64
	s_nop 0
	v_addc_co_u32_e32 v53, vcc, 0, v61, vcc
	v_add_co_u32_e32 v56, vcc, s79, v60
	global_load_dwordx4 v[32:35], v80, s[68:69]
	s_nop 0
	v_addc_co_u32_e32 v57, vcc, 0, v61, vcc
	v_add_co_u32_e32 v60, vcc, s80, v60
	global_load_dwordx4 v[36:39], v[36:37], off
	s_nop 0
	global_load_dwordx4 v[40:43], v[40:41], off
	v_addc_co_u32_e32 v61, vcc, 0, v61, vcc
	global_load_dwordx4 v[44:47], v[44:45], off
	s_nop 0
	global_load_dwordx4 v[48:51], v[48:49], off
	s_nop 0
	global_load_dwordx4 v[52:55], v[52:53], off
	s_nop 0
	global_load_dwordx4 v[56:59], v[56:57], off
	s_and_b64 vcc, exec, s[60:61]
	global_load_dwordx4 v[60:63], v[60:61], off
	s_nop 0
	ds_read_u16 v64, v154
	ds_read_u16 v65, v154 offset:288
	ds_read_u16 v66, v154 offset:576
	ds_read_u16 v67, v154 offset:864
	ds_read_u16 v68, v154 offset:1152
	ds_read_u16 v69, v154 offset:1440
	ds_read_u16 v70, v154 offset:1728
	ds_read_u16 v71, v154 offset:2016
	ds_read_u16 v84, v154 offset:2304
	ds_read_u16 v85, v154 offset:2592
	ds_read_u16 v86, v154 offset:2880
	ds_read_u16 v87, v154 offset:3168
	ds_read_u16 v88, v154 offset:3456
	ds_read_u16 v89, v154 offset:3744
	ds_read_u16 v90, v154 offset:4032
	ds_read_u16 v91, v154 offset:4320
	ds_read_u16 v72, v154 offset:18432
	ds_read_u16 v73, v154 offset:18720
	ds_read_u16 v74, v154 offset:19008
	ds_read_u16 v75, v154 offset:19296
	ds_read_u16 v76, v154 offset:19584
	ds_read_u16 v77, v154 offset:19872
	ds_read_u16 v78, v154 offset:20160
	ds_read_u16 v79, v154 offset:20448
	ds_read_u16 v92, v154 offset:20736
	ds_read_u16 v93, v154 offset:21024
	ds_read_u16 v94, v154 offset:21312
	ds_read_u16 v95, v154 offset:21600
	ds_read_u16 v96, v154 offset:21888
	ds_read_u16 v97, v154 offset:22176
	ds_read_u16 v98, v154 offset:22464
	ds_read_u16 v99, v154 offset:22752
	ds_read_u16 v176, v154 offset:36864
	ds_read_u16 v180, v154 offset:37152
	ds_read_u16 v177, v154 offset:37440
	ds_read_u16 v181, v154 offset:37728
	ds_read_u16 v178, v154 offset:38016
	ds_read_u16 v182, v154 offset:38304
	ds_read_u16 v179, v154 offset:38592
	ds_read_u16 v183, v154 offset:38880
	ds_read_u16 v168, v154 offset:39168
	ds_read_u16 v172, v154 offset:39456
	ds_read_u16 v169, v154 offset:39744
	ds_read_u16 v173, v154 offset:40032
	ds_read_u16 v170, v154 offset:40320
	ds_read_u16 v174, v154 offset:40608
	ds_read_u16 v171, v154 offset:40896
	ds_read_u16 v175, v154 offset:41184
	s_waitcnt lgkmcnt(0)
	s_barrier
	s_waitcnt lgkmcnt(14)
	v_lshlrev_b32_e32 v123, 16, v74
	v_lshlrev_b32_e32 v122, 16, v72
	v_lshlrev_b32_e32 v121, 16, v75
	v_lshlrev_b32_e32 v120, 16, v73
	v_lshlrev_b32_e32 v115, 16, v78
	v_lshlrev_b32_e32 v114, 16, v76
	v_lshlrev_b32_e32 v113, 16, v79
	v_lshlrev_b32_e32 v112, 16, v77
	v_lshlrev_b32_e32 v109, 16, v94
	v_lshlrev_b32_e32 v108, 16, v92
	v_lshlrev_b32_e32 v107, 16, v95
	v_lshlrev_b32_e32 v106, 16, v93
	v_lshlrev_b32_e32 v105, 16, v98
	v_lshlrev_b32_e32 v104, 16, v96
	v_lshlrev_b32_e32 v103, 16, v99
	v_lshlrev_b32_e32 v102, 16, v97
	v_lshlrev_b32_e32 v79, 16, v64
	v_lshlrev_b32_e32 v78, 16, v65
	v_lshlrev_b32_e32 v77, 16, v66
	v_lshlrev_b32_e32 v76, 16, v67
	v_lshlrev_b32_e32 v75, 16, v68
	v_lshlrev_b32_e32 v74, 16, v69
	v_lshlrev_b32_e32 v73, 16, v70
	v_lshlrev_b32_e32 v72, 16, v71
	v_lshlrev_b32_e32 v71, 16, v84
	v_lshlrev_b32_e32 v70, 16, v85
	v_lshlrev_b32_e32 v69, 16, v86
	v_lshlrev_b32_e32 v68, 16, v87
	v_lshlrev_b32_e32 v67, 16, v88
	v_lshlrev_b32_e32 v66, 16, v89
	v_lshlrev_b32_e32 v65, 16, v90
	v_lshlrev_b32_e32 v64, 16, v91
	s_mov_b64 s[68:69], -1
	s_cbranch_vccz .LBB0_453
	v_pk_mul_f32 v[84:85], v[122:123], s[66:67] op_sel_hi:[1,0]
	v_pk_mul_f32 v[86:87], v[120:121], s[66:67] op_sel_hi:[1,0]
	v_pk_mul_f32 v[88:89], v[114:115], s[66:67] op_sel_hi:[1,0]
	v_pk_mul_f32 v[90:91], v[112:113], s[66:67] op_sel_hi:[1,0]
	v_pk_mul_f32 v[92:93], v[108:109], s[66:67] op_sel_hi:[1,0]
	v_pk_mul_f32 v[94:95], v[106:107], s[66:67] op_sel_hi:[1,0]
	v_pk_mul_f32 v[98:99], v[104:105], s[66:67] op_sel_hi:[1,0]
	v_pk_mul_f32 v[96:97], v[102:103], s[66:67] op_sel_hi:[1,0]
	s_mov_b64 s[68:69], 0

.LBB0_455:
	v_mul_f32_e32 v121, v110, v100
	v_mul_f32_e32 v120, v101, v121
	v_mul_f32_e32 v115, v111, v120
	v_mul_f32_e32 v114, v116, v115
	v_mul_f32_e32 v113, v118, v114
	v_mul_f32_e32 v112, v117, v113
	v_mul_f32_e32 v111, v119, v112
	v_mul_f32_e32 v110, v124, v111
	v_mul_f32_e32 v109, v126, v110
	v_mul_f32_e32 v108, v125, v109
	v_mul_f32_e32 v107, v127, v108
	v_lshlrev_b32_e32 v102, 16, v180
	v_mul_f32_e32 v106, v132, v107
	v_or_b32_sdwa v116, v102, v176 dst_sel:DWORD dst_unused:UNUSED_PAD src0_sel:DWORD src1_sel:WORD_0
	s_waitcnt lgkmcnt(12)
	v_lshlrev_b32_e32 v102, 16, v181
	v_mul_f32_e32 v105, v134, v106
	v_or_b32_sdwa v117, v102, v177 dst_sel:DWORD dst_unused:UNUSED_PAD src0_sel:DWORD src1_sel:WORD_0
	s_waitcnt lgkmcnt(10)
	v_lshlrev_b32_e32 v102, 16, v182
	v_mul_f32_e32 v104, v133, v105
	v_or_b32_sdwa v118, v102, v178 dst_sel:DWORD dst_unused:UNUSED_PAD src0_sel:DWORD src1_sel:WORD_0
	s_waitcnt lgkmcnt(8)
	v_lshlrev_b32_e32 v102, 16, v183
	v_mul_f32_e32 v101, v135, v104
	v_or_b32_sdwa v119, v102, v179 dst_sel:DWORD dst_unused:UNUSED_PAD src0_sel:DWORD src1_sel:WORD_0
	s_waitcnt lgkmcnt(6)
	v_lshlrev_b32_e32 v102, 16, v172
	ds_write_b32 v143, v101
	ds_write_b128 v155, v[116:119] offset:55296
	v_or_b32_sdwa v116, v102, v168 dst_sel:DWORD dst_unused:UNUSED_PAD src0_sel:DWORD src1_sel:WORD_0
	s_waitcnt lgkmcnt(6)
	v_lshlrev_b32_e32 v102, 16, v173
	v_or_b32_sdwa v117, v102, v169 dst_sel:DWORD dst_unused:UNUSED_PAD src0_sel:DWORD src1_sel:WORD_0
	s_waitcnt lgkmcnt(4)
	v_lshlrev_b32_e32 v102, 16, v174
	v_or_b32_sdwa v118, v102, v170 dst_sel:DWORD dst_unused:UNUSED_PAD src0_sel:DWORD src1_sel:WORD_0
	s_waitcnt lgkmcnt(2)
	v_lshlrev_b32_e32 v102, 16, v175
	v_or_b32_sdwa v119, v102, v171 dst_sel:DWORD dst_unused:UNUSED_PAD src0_sel:DWORD src1_sel:WORD_0
	ds_write_b128 v155, v[116:119] offset:55312
	s_waitcnt vmcnt(15)
	v_cvt_pk_bf16_f32 v102, v28, v29
	v_cvt_pk_bf16_f32 v103, v30, v31
	s_waitcnt vmcnt(14)
	v_cvt_pk_bf16_f32 v116, v24, v25
	v_cvt_pk_bf16_f32 v117, v26, v27
	ds_write2_b64 v156, v[102:103], v[116:117] offset1:4
	s_waitcnt vmcnt(13)
	v_cvt_pk_bf16_f32 v102, v20, v21
	v_cvt_pk_bf16_f32 v103, v22, v23
	s_waitcnt vmcnt(12)
	v_cvt_pk_bf16_f32 v116, v16, v17
	v_cvt_pk_bf16_f32 v117, v18, v19
	ds_write2_b64 v156, v[102:103], v[116:117] offset0:8 offset1:12
	s_waitcnt vmcnt(11)
	v_cvt_pk_bf16_f32 v102, v12, v13
	v_cvt_pk_bf16_f32 v103, v14, v15
	s_waitcnt vmcnt(10)
	v_cvt_pk_bf16_f32 v116, v8, v9
	v_cvt_pk_bf16_f32 v117, v10, v11
	ds_write2_b64 v156, v[102:103], v[116:117] offset0:16 offset1:20
	s_waitcnt vmcnt(9)
	v_cvt_pk_bf16_f32 v102, v0, v1
	v_cvt_pk_bf16_f32 v103, v2, v3
	s_waitcnt vmcnt(8)
	v_cvt_pk_bf16_f32 v116, v4, v5
	v_cvt_pk_bf16_f32 v117, v6, v7
	ds_write2_b64 v156, v[102:103], v[116:117] offset0:24 offset1:28
	s_waitcnt lgkmcnt(0)
	s_barrier
	v_mov_b32_e32 v116, 1.0
	s_and_saveexec_b64 s[68:69], s[6:7]
	ds_read_b32 v116, v144
	s_or_b64 exec, exec, s[68:69]
	ds_read_b32 v102, v144 offset:512
	s_and_saveexec_b64 s[68:69], s[10:11]
	s_cbranch_execz .LBB0_459
	s_waitcnt lgkmcnt(0)
	v_mul_f32_e32 v116, v116, v102
